# in-proj V epilogue: row-major ds_write2_b32 staging + ds_read_b64_tr_b16 transpose reads instead of ds_write_b16 scatter
# speedup vs baseline: 1.0049x; 1.0049x over previous
.LBB0_585:
	s_and_b64 vcc, exec, s[8:9]
	s_cbranch_vccz .LBB0_656
	v_lshl_add_u32 v140, v229, 1, v234
	v_bfe_u32 v141, v217, 2, 2
	v_mul_u32_u24_e32 v141, 0x88, v141
	v_and_b32_e32 v142, 0x30, v217
	v_lshl_add_u32 v141, v142, 1, v141
	v_and_b32_e32 v142, 3, v217
	v_lshl_add_u32 v141, v142, 3, v141
	v_lshlrev_b32_e32 v142, 1, v187
	v_sub_u32_e32 v142, v235, v142
	v_add_u32_e32 v141, v141, v142
	v_cvt_pk_bf16_f32 v12, v126, v127
	s_add_i32 s0, s27, s25
	v_cvt_pk_bf16_f32 v126, v128, v129
	ds_write2_b32 v140, v12, v126 offset0:0 offset1:1
	v_cvt_pk_bf16_f32 v12, v122, v123
	s_lshl_b32 s0, s0, 3
	v_cvt_pk_bf16_f32 v122, v124, v125
	ds_write2_b32 v140, v12, v122 offset0:8 offset1:9
	v_cvt_pk_bf16_f32 v12, v114, v115
	s_add_i32 s0, s0, s69
	v_cvt_pk_bf16_f32 v114, v116, v117
	ds_write2_b32 v140, v12, v114 offset0:16 offset1:17
	v_cvt_pk_bf16_f32 v12, v106, v107
	s_mul_hi_i32 s1, s0, 0x48000
	s_mul_i32 s0, s0, 0x48000
	v_cvt_pk_bf16_f32 v106, v108, v109
	ds_write2_b32 v140, v12, v106 offset0:24 offset1:25
	s_add_u32 s8, s60, s0
	s_addc_u32 s9, s61, s1
	s_add_i32 s0, s68, s64
	ds_read_b64_tr_b16 v[106:107], v141
	ds_read_b64_tr_b16 v[108:109], v141 offset:544
	ds_read_b64_tr_b16 v[114:115], v141 offset:1088
	ds_read_b64_tr_b16 v[116:117], v141 offset:1632
	s_ashr_i32 s1, s0, 31
	s_lshl_b64 s[0:1], s[0:1], 7
	s_add_u32 s0, s8, s0
	s_addc_u32 s1, s9, s1
	v_lshlrev_b32_e32 v12, 1, v186
	s_waitcnt lgkmcnt(0)
	global_store_dwordx4 v12, v[106:109], s[0:1]
	global_store_dwordx4 v12, v[114:117], s[0:1] offset:16
	v_cvt_pk_bf16_f32 v98, v98, v99
	v_cvt_pk_bf16_f32 v106, v118, v119
	v_cvt_pk_bf16_f32 v107, v120, v121
	ds_write2_b32 v140, v106, v107 offset0:0 offset1:1
	v_cvt_pk_bf16_f32 v106, v110, v111
	v_cvt_pk_bf16_f32 v90, v90, v91
	v_cvt_pk_bf16_f32 v107, v112, v113
	ds_write2_b32 v140, v106, v107 offset0:8 offset1:9
	v_cvt_pk_bf16_f32 v99, v100, v101
	ds_write2_b32 v140, v98, v99 offset0:16 offset1:17
	v_cvt_pk_bf16_f32 v91, v92, v93
	ds_write2_b32 v140, v90, v91 offset0:24 offset1:25
	ds_read_b64_tr_b16 v[90:91], v141
	ds_read_b64_tr_b16 v[92:93], v141 offset:544
	ds_read_b64_tr_b16 v[98:99], v141 offset:1088
	ds_read_b64_tr_b16 v[100:101], v141 offset:1632
	v_lshl_add_u64 v[106:107], s[0:1], 0, v[12:13]
	s_waitcnt lgkmcnt(0)
	global_store_dwordx4 v12, v[90:93], s[0:1] offset:2048
	global_store_dwordx4 v12, v[98:101], s[0:1] offset:2064
	v_cvt_pk_bf16_f32 v12, v102, v103
	v_cvt_pk_bf16_f32 v90, v104, v105
	ds_write2_b32 v140, v12, v90 offset0:0 offset1:1
	v_cvt_pk_bf16_f32 v12, v94, v95
	v_cvt_pk_bf16_f32 v90, v96, v97
	ds_write2_b32 v140, v12, v90 offset0:8 offset1:9
	v_cvt_pk_bf16_f32 v12, v82, v83
	v_cvt_pk_bf16_f32 v82, v84, v85
	ds_write2_b32 v140, v12, v82 offset0:16 offset1:17
	v_cvt_pk_bf16_f32 v12, v74, v75
	v_cvt_pk_bf16_f32 v74, v76, v77
	ds_write2_b32 v140, v12, v74 offset0:24 offset1:25
	ds_read_b64_tr_b16 v[74:75], v141
	ds_read_b64_tr_b16 v[76:77], v141 offset:544
	ds_read_b64_tr_b16 v[82:83], v141 offset:1088
	ds_read_b64_tr_b16 v[84:85], v141 offset:1632
	v_add_co_u32_e32 v90, vcc, s86, v106
	v_cvt_pk_bf16_f32 v12, v86, v87
	s_nop 0
	v_addc_co_u32_e32 v91, vcc, 0, v107, vcc
	s_waitcnt lgkmcnt(0)
	global_store_dwordx4 v[90:91], v[74:77], off
	global_store_dwordx4 v[90:91], v[82:85], off offset:16
	s_movk_i32 s0, 0x4000
	v_cvt_pk_bf16_f32 v74, v88, v89
	ds_write2_b32 v140, v12, v74 offset0:0 offset1:1
	v_cvt_pk_bf16_f32 v12, v78, v79
	v_cvt_pk_bf16_f32 v74, v80, v81
	ds_write2_b32 v140, v12, v74 offset0:8 offset1:9
	v_cvt_pk_bf16_f32 v12, v70, v71
	v_cvt_pk_bf16_f32 v70, v72, v73
	ds_write2_b32 v140, v12, v70 offset0:16 offset1:17
	v_cvt_pk_bf16_f32 v12, v66, v67
	v_cvt_pk_bf16_f32 v66, v68, v69
	ds_write2_b32 v140, v12, v66 offset0:24 offset1:25
	ds_read_b64_tr_b16 v[66:67], v141
	ds_read_b64_tr_b16 v[68:69], v141 offset:544
	ds_read_b64_tr_b16 v[70:71], v141 offset:1088
	ds_read_b64_tr_b16 v[72:73], v141 offset:1632
	v_cvt_pk_bf16_f32 v12, v62, v63
	s_waitcnt lgkmcnt(0)
	global_store_dwordx4 v[90:91], v[66:69], off offset:2048
	global_store_dwordx4 v[90:91], v[70:73], off offset:2064
	v_cvt_pk_bf16_f32 v62, v64, v65
	ds_write2_b32 v140, v12, v62 offset0:0 offset1:1
	v_cvt_pk_bf16_f32 v12, v58, v59
	v_cvt_pk_bf16_f32 v58, v60, v61
	ds_write2_b32 v140, v12, v58 offset0:8 offset1:9
	v_cvt_pk_bf16_f32 v12, v54, v55
	v_cvt_pk_bf16_f32 v54, v56, v57
	ds_write2_b32 v140, v12, v54 offset0:16 offset1:17
	v_cvt_pk_bf16_f32 v12, v46, v47
	v_cvt_pk_bf16_f32 v46, v48, v49
	ds_write2_b32 v140, v12, v46 offset0:24 offset1:25
	ds_read_b64_tr_b16 v[46:47], v141
	ds_read_b64_tr_b16 v[48:49], v141 offset:544
	ds_read_b64_tr_b16 v[54:55], v141 offset:1088
	ds_read_b64_tr_b16 v[56:57], v141 offset:1632
	v_add_co_u32_e32 v58, vcc, s0, v106
	v_cvt_pk_bf16_f32 v12, v50, v51
	s_nop 0
	v_addc_co_u32_e32 v59, vcc, 0, v107, vcc
	v_add_co_u32_e32 v60, vcc, s79, v106
	v_cvt_pk_bf16_f32 v8, v8, v9
	s_nop 0
	v_addc_co_u32_e32 v61, vcc, 0, v107, vcc
	s_waitcnt lgkmcnt(0)
	global_store_dwordx4 v[60:61], v[46:49], off offset:-4096
	global_store_dwordx4 v[58:59], v[54:57], off offset:16
	v_cvt_pk_bf16_f32 v9, v10, v11
	v_cvt_pk_bf16_f32 v46, v52, v53
	ds_write2_b32 v140, v12, v46 offset0:0 offset1:1
	v_cvt_pk_bf16_f32 v12, v42, v43
	v_cvt_pk_bf16_f32 v42, v44, v45
	ds_write2_b32 v140, v12, v42 offset0:8 offset1:9
	v_cvt_pk_bf16_f32 v12, v34, v35
	v_cvt_pk_bf16_f32 v34, v36, v37
	ds_write2_b32 v140, v12, v34 offset0:16 offset1:17
	v_cvt_pk_bf16_f32 v12, v26, v27
	v_cvt_pk_bf16_f32 v26, v28, v29
	ds_write2_b32 v140, v12, v26 offset0:24 offset1:25
	ds_read_b64_tr_b16 v[26:27], v141
	ds_read_b64_tr_b16 v[28:29], v141 offset:544
	ds_read_b64_tr_b16 v[34:35], v141 offset:1088
	ds_read_b64_tr_b16 v[36:37], v141 offset:1632
	v_cvt_pk_bf16_f32 v12, v38, v39
	s_waitcnt lgkmcnt(0)
	global_store_dwordx4 v[58:59], v[26:29], off offset:2048
	global_store_dwordx4 v[58:59], v[34:37], off offset:2064
	s_nop 0
	v_cvt_pk_bf16_f32 v26, v40, v41
	ds_write2_b32 v140, v12, v26 offset0:0 offset1:1
	v_cvt_pk_bf16_f32 v12, v30, v31
	v_cvt_pk_bf16_f32 v26, v32, v33
	ds_write2_b32 v140, v12, v26 offset0:8 offset1:9
	v_cvt_pk_bf16_f32 v12, v18, v19
	v_cvt_pk_bf16_f32 v18, v20, v21
	ds_write2_b32 v140, v12, v18 offset0:16 offset1:17
	ds_write2_b32 v140, v8, v9 offset0:24 offset1:25
	ds_read_b64_tr_b16 v[8:9], v141
	ds_read_b64_tr_b16 v[10:11], v141 offset:544
	ds_read_b64_tr_b16 v[18:19], v141 offset:1088
	ds_read_b64_tr_b16 v[20:21], v141 offset:1632
	s_waitcnt lgkmcnt(0)
	global_store_dwordx4 v[60:61], v[8:11], off
	global_store_dwordx4 v[60:61], v[18:21], off offset:16
	s_nop 0
	v_cvt_pk_bf16_f32 v8, v22, v23
	v_cvt_pk_bf16_f32 v9, v24, v25
	ds_write2_b32 v140, v8, v9 offset0:0 offset1:1
	v_cvt_pk_bf16_f32 v8, v14, v15
	v_cvt_pk_bf16_f32 v4, v4, v5
	v_cvt_pk_bf16_f32 v0, v0, v1
	v_cvt_pk_bf16_f32 v9, v16, v17
	ds_write2_b32 v140, v8, v9 offset0:8 offset1:9
	v_cvt_pk_bf16_f32 v5, v6, v7
	ds_write2_b32 v140, v4, v5 offset0:16 offset1:17
	v_cvt_pk_bf16_f32 v1, v2, v3
	ds_write2_b32 v140, v0, v1 offset0:24 offset1:25
	ds_read_b64_tr_b16 v[0:1], v141
	ds_read_b64_tr_b16 v[2:3], v141 offset:544
	ds_read_b64_tr_b16 v[4:5], v141 offset:1088
	ds_read_b64_tr_b16 v[6:7], v141 offset:1632
	s_waitcnt lgkmcnt(0)
	global_store_dwordx4 v[60:61], v[0:3], off offset:2048
	global_store_dwordx4 v[60:61], v[4:7], off offset:2064
	s_andn2_b64 vcc, exec, s[6:7]
	s_mov_b64 s[0:1], -1
	s_cbranch_vccnz .LBB0_563
	s_branch .LBB0_657
